# attention Y stage: K/V prefetch addresses formed with scalar adds plus one 64-bit vector add each (was carry-chain VALU with s_nop pads)
# baseline (speedup 1.0000x reference)
; #define LAS __attribute__((address_space(3)))
; #define SBAR() __builtin_amdgcn_sched_barrier(0)
; __device__ __forceinline__ void qkt(f32x16& p0, f32x16& p1, const LAS char* Ks, const bf16x8* qr, const f32x16& negm, int r32, int hi) {
; #pragma unroll
;     for (int d0 = 0; d0 < 4; ++d0) { const int cb = (d0 * 16 + hi * 8) * 2;
;         const bf16x8 b0 = *(const LAS bf16x8*)(Ks + KSWZ(r32, cb));
;         const bf16x8 b1 = *(const LAS bf16x8*)(Ks + KSWZ(32 + r32, cb));
;         if (d0 == 0) { p0 = __builtin_amdgcn_mfma_f32_32x32x16_bf16(b0, qr[0], negm, 0, 0, 0); p1 = __builtin_amdgcn_mfma_f32_32x32x16_bf16(b1, qr[0], negm, 0, 0, 0); }
;         else { p0 = __builtin_amdgcn_mfma_f32_32x32x16_bf16(b0, qr[d0], p0, 0, 0, 0); p1 = __builtin_amdgcn_mfma_f32_32x32x16_bf16(b1, qr[d0], p1, 0, 0, 0); } }
; }
; __device__ __forceinline__ int v_st(int k, int c) { const int kk = (k & ~0xC) | ((k & 4) << 1) | ((k & 8) >> 1); return ((kk >> 3) * 4 + (c >> 5)) * 512 + ((kk & 7) * 32 + (c & 31)) * 2; }
; __device__ __forceinline__ int v_rd_base(int lane) { return ((lane & 3) << 3) | (((lane >> 2) & 3) << 6) | (((lane >> 4) & 1) << 5) | (((lane >> 5) & 1) << 8); }
; template <int OFF> __device__ __forceinline__ s16x4 tr_read(int vb) {
;     s16x4 r; asm volatile("ds_read_b64_tr_b16 %0, %1 offset:%2" : "=&v"(r) : "v"(vb), "i"(OFF) : "memory"); return r;
; }
; template <int D0> __device__ __forceinline__ void pv_one(f32x16& od, int vb, bf16x8 pa0, bf16x8 pa1, bf16x8 pa2, bf16x8 pa3) {
;     const s16x4 l0 = tr_read<v_rd_off(D0, 0, 0)>(vb), h0 = tr_read<v_rd_off(D0, 0, 1)>(vb), l1 = tr_read<v_rd_off(D0, 1, 0)>(vb), h1 = tr_read<v_rd_off(D0, 1, 1)>(vb);
;     const s16x4 l2 = tr_read<v_rd_off(D0, 2, 0)>(vb), h2 = tr_read<v_rd_off(D0, 2, 1)>(vb), l3 = tr_read<v_rd_off(D0, 3, 0)>(vb), h3 = tr_read<v_rd_off(D0, 3, 1)>(vb);
;     asm volatile("s_waitcnt lgkmcnt(0)" ::: "memory"); SBAR();
;     ...
;     od = __builtin_amdgcn_mfma_f32_32x32x16_bf16(pa0, PK(l0, h0), od, 0, 0, 0);
;     od = __builtin_amdgcn_mfma_f32_32x32x16_bf16(pa1, PK(l1, h1), od, 0, 0, 0);
;     od = __builtin_amdgcn_mfma_f32_32x32x16_bf16(pa2, PK(l2, h2), od, 0, 0, 0);
;     od = __builtin_amdgcn_mfma_f32_32x32x16_bf16(pa3, PK(l3, h3), od, 0, 0, 0);
;     ...
; }
; __device__ __forceinline__ void pv_d0(f32x16* o, int vb, bf16x8 pa0, bf16x8 pa1, bf16x8 pa2, bf16x8 pa3) {
.LBB0_591:
	s_add_i32 s2, s48, -4
	s_setprio 1
	s_and_b32 s61, s2, 3
	v_lshl_add_u32 v0, s61, 13, v241
	v_add_u32_e32 v6, v0, v237
	ds_read_b128 v[2:5], v6 offset:4096
	ds_read_b128 v[6:9], v6
	s_and_b32 s2, s39, 0xc000
	s_waitcnt lgkmcnt(1)
	v_mfma_f32_32x32x16_bf16 v[112:127], v[2:5], v[156:159], v[96:111]
	s_waitcnt lgkmcnt(0)
	v_mfma_f32_32x32x16_bf16 v[128:143], v[6:9], v[156:159], v[96:111]
	v_add_u32_e32 v6, v0, v238
	ds_read_b128 v[2:5], v6 offset:4096
	ds_read_b128 v[6:9], v6
	s_waitcnt lgkmcnt(1)
	v_mfma_f32_32x32x16_bf16 v[112:127], v[2:5], v[152:155], v[112:127]
	s_waitcnt lgkmcnt(0)
	v_mfma_f32_32x32x16_bf16 v[128:143], v[6:9], v[152:155], v[128:143]
	v_add_u32_e32 v6, v0, v239
	ds_read_b128 v[2:5], v6 offset:4096
	ds_read_b128 v[6:9], v6
	v_add_u32_e32 v0, v0, v240
	s_waitcnt lgkmcnt(1)
	v_mfma_f32_32x32x16_bf16 v[112:127], v[2:5], v[148:151], v[112:127]
	s_waitcnt lgkmcnt(0)
	v_mfma_f32_32x32x16_bf16 v[128:143], v[6:9], v[148:151], v[128:143]
	ds_read_b128 v[2:5], v0 offset:4096
	ds_read_b128 v[6:9], v0
	v_add_u32_e32 v0, s2, v242
	ds_read_b64_tr_b16 v[160:161], v0 offset:0
	ds_read_b64_tr_b16 v[162:163], v0 offset:0x800
	ds_read_b64_tr_b16 v[164:165], v0 offset:0x1000
	ds_read_b64_tr_b16 v[166:167], v0 offset:0x1800
	s_waitcnt lgkmcnt(5)
	v_mfma_f32_32x32x16_bf16 v[112:127], v[2:5], v[144:147], v[112:127]
	ds_read_b64_tr_b16 v[10:11], v0 offset:0x2000
	ds_read_b64_tr_b16 v[12:13], v0 offset:0x2800
	s_waitcnt lgkmcnt(6)
	v_mfma_f32_32x32x16_bf16 v[128:143], v[6:9], v[144:147], v[128:143]
	ds_read_b64_tr_b16 v[80:81], v0 offset:0x3000
	ds_read_b64_tr_b16 v[82:83], v0 offset:0x3800
	s_waitcnt lgkmcnt(6)
	v_mfma_f32_32x32x16_bf16 v[64:79], v[184:187], v[160:163], v[64:79]
	ds_read_b64_tr_b16 v[2:3], v0 offset:0x200
	ds_read_b64_tr_b16 v[4:5], v0 offset:0xa00
	s_waitcnt lgkmcnt(6)
	v_mfma_f32_32x32x16_bf16 v[64:79], v[188:191], v[164:167], v[64:79]
	ds_read_b64_tr_b16 v[6:7], v0 offset:0x1200
	ds_read_b64_tr_b16 v[8:9], v0 offset:0x1a00
	s_waitcnt lgkmcnt(6)
	v_mfma_f32_32x32x16_bf16 v[64:79], v[192:195], v[10:13], v[64:79]
	ds_read_b64_tr_b16 v[10:11], v0 offset:0x2200
	ds_read_b64_tr_b16 v[12:13], v0 offset:0x2a00
	s_waitcnt lgkmcnt(6)
	v_mfma_f32_32x32x16_bf16 v[64:79], v[196:199], v[80:83], v[64:79]
	ds_read_b64_tr_b16 v[80:81], v0 offset:0x3200
	ds_read_b64_tr_b16 v[82:83], v0 offset:0x3a00
	s_waitcnt lgkmcnt(6)
	v_mfma_f32_32x32x16_bf16 v[48:63], v[184:187], v[2:5], v[48:63]
	ds_read_b64_tr_b16 v[2:3], v0 offset:0x400
	ds_read_b64_tr_b16 v[4:5], v0 offset:0xc00
	s_waitcnt lgkmcnt(6)
	v_mfma_f32_32x32x16_bf16 v[48:63], v[188:191], v[6:9], v[48:63]
	ds_read_b64_tr_b16 v[6:7], v0 offset:0x1400
	ds_read_b64_tr_b16 v[8:9], v0 offset:0x1c00
	s_waitcnt lgkmcnt(6)
	v_mfma_f32_32x32x16_bf16 v[48:63], v[192:195], v[10:13], v[48:63]
	ds_read_b64_tr_b16 v[10:11], v0 offset:0x2400
	ds_read_b64_tr_b16 v[12:13], v0 offset:0x2c00
	s_waitcnt lgkmcnt(6)
	v_mfma_f32_32x32x16_bf16 v[48:63], v[196:199], v[80:83], v[48:63]
	ds_read_b64_tr_b16 v[80:81], v0 offset:0x3400
	ds_read_b64_tr_b16 v[82:83], v0 offset:0x3c00
	s_waitcnt lgkmcnt(6)
	v_mfma_f32_32x32x16_bf16 v[32:47], v[184:187], v[2:5], v[32:47]
	ds_read_b64_tr_b16 v[2:3], v0 offset:0x600
	ds_read_b64_tr_b16 v[4:5], v0 offset:0xe00
	s_waitcnt lgkmcnt(6)
	v_mfma_f32_32x32x16_bf16 v[32:47], v[188:191], v[6:9], v[32:47]
	ds_read_b64_tr_b16 v[6:7], v0 offset:0x1600
	ds_read_b64_tr_b16 v[8:9], v0 offset:0x1e00
	s_waitcnt lgkmcnt(6)
	v_mfma_f32_32x32x16_bf16 v[32:47], v[192:195], v[10:13], v[32:47]
	ds_read_b64_tr_b16 v[10:11], v0 offset:0x2600
	ds_read_b64_tr_b16 v[12:13], v0 offset:0x2e00
	s_waitcnt lgkmcnt(6)
	v_mfma_f32_32x32x16_bf16 v[32:47], v[196:199], v[80:83], v[32:47]
	ds_read_b64_tr_b16 v[80:81], v0 offset:0x3600
	ds_read_b64_tr_b16 v[82:83], v0 offset:0x3e00
	s_waitcnt lgkmcnt(6)
	v_mfma_f32_32x32x16_bf16 v[16:31], v[184:187], v[2:5], v[16:31]
	s_waitcnt lgkmcnt(4)
	v_mfma_f32_32x32x16_bf16 v[16:31], v[188:191], v[6:9], v[16:31]
	s_waitcnt lgkmcnt(2)
	v_mfma_f32_32x32x16_bf16 v[16:31], v[192:195], v[10:13], v[16:31]
	s_waitcnt lgkmcnt(0)
	v_mfma_f32_32x32x16_bf16 v[16:31], v[196:199], v[80:83], v[16:31]
	s_setprio 0
	s_add_i32 s2, s48, -2
	s_and_b32 s2, s2, 3
	s_lshl_b32 s3, s2, 14
	s_add_i32 s3, s3, 0
	s_waitcnt lgkmcnt(0)
	s_barrier
	v_add_u32_e32 v0, s3, v233
	s_add_i32 s49, s48, -1
	s_waitcnt vmcnt(2)
	ds_write_b128 v0, v[172:175]
	v_add_u32_e32 v0, s3, v234
	s_cmp_lt_u32 s49, s45
	s_waitcnt vmcnt(1)
	ds_write_b128 v0, v[176:179]
	v_lshl_add_u32 v0, s2, 13, v235
	s_cselect_b64 s[2:3], -1, 0
	s_cmp_ge_u32 s49, s45
	s_waitcnt vmcnt(0)
	ds_write_b128 v0, v[180:183]
	s_cbranch_scc1 .LBB0_593
	s_add_u32 s4, s36, 0xef40000
	s_addc_u32 s5, s37, 0
	v_lshl_add_u64 v[2:3], v[218:219], 0, s[4:5]
	s_add_u32 s4, s4, 0x8000
	s_addc_u32 s5, s5, 0
	v_lshl_add_u64 v[4:5], v[218:219], 0, s[4:5]
	global_load_dwordx4 v[160:163], v[2:3], off
	global_load_dwordx4 v[164:167], v[4:5], off
	s_add_u32 s4, s36, 0xcf40000
	s_addc_u32 s5, s37, 0
	v_lshl_add_u64 v[2:3], v[216:217], 0, s[4:5]
	global_load_dwordx4 v[168:171], v[2:3], off

; #define SLOAD(i, k0) do { sr_[i].vs0 = *(const bf16x8*)(&Vh[(size_t)((k0) + sr) * LDX + sc]); sr_[i].vs1 = *(const bf16x8*)(&Vh[(size_t)((k0) + 32 + sr) * LDX + sc]); \
;     sr_[i].ks0 = *(const bf16x8*)(&Kh[(size_t)((k0) + kr) * LDX + kc]); } while (0)
; __device__ __forceinline__ void attn_pass(const bf16_t* __restrict__ Qb, const bf16_t* __restrict__ Kh, const bf16_t* __restrict__ Vh, int seq, LAS char* lds, const int wid, f32x16 (&o)[4], float (&rli)[16]) {
;     ...
;         if (j + 4 < NT) SLOAD(1, (j + 4) * KVBLK);
.LBB0_600:
	s_cmp_ge_u32 s48, s45
	s_cbranch_scc1 .LBB0_602
	s_add_u32 s4, s36, 0xef50000
	s_addc_u32 s5, s37, 0
	v_lshl_add_u64 v[2:3], v[218:219], 0, s[4:5]
	s_add_u32 s4, s4, 0x8000
	s_addc_u32 s5, s5, 0
	v_lshl_add_u64 v[4:5], v[218:219], 0, s[4:5]
	global_load_dwordx4 v[172:175], v[2:3], off
	global_load_dwordx4 v[176:179], v[4:5], off
	s_add_u32 s4, s36, 0xcf50000
	s_addc_u32 s5, s37, 0
	v_lshl_add_u64 v[2:3], v[216:217], 0, s[4:5]
	global_load_dwordx4 v[180:183], v[2:3], off

; #define LAS __attribute__((address_space(3)))
; #define SBAR() __builtin_amdgcn_sched_barrier(0)
; __device__ __forceinline__ void qkt(f32x16& p0, f32x16& p1, const LAS char* Ks, const bf16x8* qr, const f32x16& negm, int r32, int hi) {
; #pragma unroll
;     for (int d0 = 0; d0 < 4; ++d0) { const int cb = (d0 * 16 + hi * 8) * 2;
;         const bf16x8 b0 = *(const LAS bf16x8*)(Ks + KSWZ(r32, cb));
;         const bf16x8 b1 = *(const LAS bf16x8*)(Ks + KSWZ(32 + r32, cb));
;         if (d0 == 0) { p0 = __builtin_amdgcn_mfma_f32_32x32x16_bf16(b0, qr[0], negm, 0, 0, 0); p1 = __builtin_amdgcn_mfma_f32_32x32x16_bf16(b1, qr[0], negm, 0, 0, 0); }
;         else { p0 = __builtin_amdgcn_mfma_f32_32x32x16_bf16(b0, qr[d0], p0, 0, 0, 0); p1 = __builtin_amdgcn_mfma_f32_32x32x16_bf16(b1, qr[d0], p1, 0, 0, 0); } }
; }
; __device__ __forceinline__ int v_st(int k, int c) { const int kk = (k & ~0xC) | ((k & 4) << 1) | ((k & 8) >> 1); return ((kk >> 3) * 4 + (c >> 5)) * 512 + ((kk & 7) * 32 + (c & 31)) * 2; }
; __device__ __forceinline__ int v_rd_base(int lane) { return ((lane & 3) << 3) | (((lane >> 2) & 3) << 6) | (((lane >> 4) & 1) << 5) | (((lane >> 5) & 1) << 8); }
; template <int OFF> __device__ __forceinline__ s16x4 tr_read(int vb) {
;     s16x4 r; asm volatile("ds_read_b64_tr_b16 %0, %1 offset:%2" : "=&v"(r) : "v"(vb), "i"(OFF) : "memory"); return r;
; }
; template <int D0> __device__ __forceinline__ void pv_one(f32x16& od, int vb, bf16x8 pa0, bf16x8 pa1, bf16x8 pa2, bf16x8 pa3) {
;     const s16x4 l0 = tr_read<v_rd_off(D0, 0, 0)>(vb), h0 = tr_read<v_rd_off(D0, 0, 1)>(vb), l1 = tr_read<v_rd_off(D0, 1, 0)>(vb), h1 = tr_read<v_rd_off(D0, 1, 1)>(vb);
;     const s16x4 l2 = tr_read<v_rd_off(D0, 2, 0)>(vb), h2 = tr_read<v_rd_off(D0, 2, 1)>(vb), l3 = tr_read<v_rd_off(D0, 3, 0)>(vb), h3 = tr_read<v_rd_off(D0, 3, 1)>(vb);
;     asm volatile("s_waitcnt lgkmcnt(0)" ::: "memory"); SBAR();
;     ...
;     od = __builtin_amdgcn_mfma_f32_32x32x16_bf16(pa0, PK(l0, h0), od, 0, 0, 0);
;     od = __builtin_amdgcn_mfma_f32_32x32x16_bf16(pa1, PK(l1, h1), od, 0, 0, 0);
;     od = __builtin_amdgcn_mfma_f32_32x32x16_bf16(pa2, PK(l2, h2), od, 0, 0, 0);
;     od = __builtin_amdgcn_mfma_f32_32x32x16_bf16(pa3, PK(l3, h3), od, 0, 0, 0);
;     ...
; }
; __device__ __forceinline__ void pv_d0(f32x16* o, int vb, bf16x8 pa0, bf16x8 pa1, bf16x8 pa2, bf16x8 pa3) {
.LBB0_622:
	s_add_i32 s2, s34, -4
	s_setprio 1
	s_and_b32 s38, s2, 3
	v_lshl_add_u32 v0, s38, 13, v241
	v_add_u32_e32 v6, v0, v240
	ds_read_b128 v[2:5], v6 offset:4096
	ds_read_b128 v[6:9], v6
	s_and_b32 s2, s19, 0xc000
	s_waitcnt lgkmcnt(1)
	v_mfma_f32_32x32x16_bf16 v[112:127], v[2:5], v[156:159], v[96:111]
	s_waitcnt lgkmcnt(0)
	v_mfma_f32_32x32x16_bf16 v[128:143], v[6:9], v[156:159], v[96:111]
	v_add_u32_e32 v6, v0, v239
	ds_read_b128 v[2:5], v6 offset:4096
	ds_read_b128 v[6:9], v6
	s_waitcnt lgkmcnt(1)
	v_mfma_f32_32x32x16_bf16 v[112:127], v[2:5], v[152:155], v[112:127]
	s_waitcnt lgkmcnt(0)
	v_mfma_f32_32x32x16_bf16 v[128:143], v[6:9], v[152:155], v[128:143]
	v_add_u32_e32 v6, v0, v236
	ds_read_b128 v[2:5], v6 offset:4096
	ds_read_b128 v[6:9], v6
	v_add_u32_e32 v0, v0, v237
	s_waitcnt lgkmcnt(1)
	v_mfma_f32_32x32x16_bf16 v[112:127], v[2:5], v[148:151], v[112:127]
	s_waitcnt lgkmcnt(0)
	v_mfma_f32_32x32x16_bf16 v[128:143], v[6:9], v[148:151], v[128:143]
	ds_read_b128 v[2:5], v0 offset:4096
	ds_read_b128 v[6:9], v0
	v_add_u32_e32 v0, s2, v242
	ds_read_b64_tr_b16 v[160:161], v0 offset:0
	ds_read_b64_tr_b16 v[162:163], v0 offset:0x800
	ds_read_b64_tr_b16 v[164:165], v0 offset:0x1000
	ds_read_b64_tr_b16 v[166:167], v0 offset:0x1800
	s_waitcnt lgkmcnt(5)
	v_mfma_f32_32x32x16_bf16 v[112:127], v[2:5], v[144:147], v[112:127]
	ds_read_b64_tr_b16 v[10:11], v0 offset:0x2000
	ds_read_b64_tr_b16 v[12:13], v0 offset:0x2800
	s_waitcnt lgkmcnt(6)
	v_mfma_f32_32x32x16_bf16 v[128:143], v[6:9], v[144:147], v[128:143]
	ds_read_b64_tr_b16 v[80:81], v0 offset:0x3000
	ds_read_b64_tr_b16 v[82:83], v0 offset:0x3800
	s_waitcnt lgkmcnt(6)
	v_mfma_f32_32x32x16_bf16 v[64:79], v[184:187], v[160:163], v[64:79]
	ds_read_b64_tr_b16 v[2:3], v0 offset:0x200
	ds_read_b64_tr_b16 v[4:5], v0 offset:0xa00
	s_waitcnt lgkmcnt(6)
	v_mfma_f32_32x32x16_bf16 v[64:79], v[188:191], v[164:167], v[64:79]
	ds_read_b64_tr_b16 v[6:7], v0 offset:0x1200
	ds_read_b64_tr_b16 v[8:9], v0 offset:0x1a00
	s_waitcnt lgkmcnt(6)
	v_mfma_f32_32x32x16_bf16 v[64:79], v[192:195], v[10:13], v[64:79]
	ds_read_b64_tr_b16 v[10:11], v0 offset:0x2200
	ds_read_b64_tr_b16 v[12:13], v0 offset:0x2a00
	s_waitcnt lgkmcnt(6)
	v_mfma_f32_32x32x16_bf16 v[64:79], v[196:199], v[80:83], v[64:79]
	ds_read_b64_tr_b16 v[80:81], v0 offset:0x3200
	ds_read_b64_tr_b16 v[82:83], v0 offset:0x3a00
	s_waitcnt lgkmcnt(6)
	v_mfma_f32_32x32x16_bf16 v[48:63], v[184:187], v[2:5], v[48:63]
	ds_read_b64_tr_b16 v[2:3], v0 offset:0x400
	ds_read_b64_tr_b16 v[4:5], v0 offset:0xc00
	s_waitcnt lgkmcnt(6)
	v_mfma_f32_32x32x16_bf16 v[48:63], v[188:191], v[6:9], v[48:63]
	ds_read_b64_tr_b16 v[6:7], v0 offset:0x1400
	ds_read_b64_tr_b16 v[8:9], v0 offset:0x1c00
	s_waitcnt lgkmcnt(6)
	v_mfma_f32_32x32x16_bf16 v[48:63], v[192:195], v[10:13], v[48:63]
	ds_read_b64_tr_b16 v[10:11], v0 offset:0x2400
	ds_read_b64_tr_b16 v[12:13], v0 offset:0x2c00
	s_waitcnt lgkmcnt(6)
	v_mfma_f32_32x32x16_bf16 v[48:63], v[196:199], v[80:83], v[48:63]
	ds_read_b64_tr_b16 v[80:81], v0 offset:0x3400
	ds_read_b64_tr_b16 v[82:83], v0 offset:0x3c00
	s_waitcnt lgkmcnt(6)
	v_mfma_f32_32x32x16_bf16 v[32:47], v[184:187], v[2:5], v[32:47]
	ds_read_b64_tr_b16 v[2:3], v0 offset:0x600
	ds_read_b64_tr_b16 v[4:5], v0 offset:0xe00
	s_waitcnt lgkmcnt(6)
	v_mfma_f32_32x32x16_bf16 v[32:47], v[188:191], v[6:9], v[32:47]
	ds_read_b64_tr_b16 v[6:7], v0 offset:0x1600
	ds_read_b64_tr_b16 v[8:9], v0 offset:0x1e00
	s_waitcnt lgkmcnt(6)
	v_mfma_f32_32x32x16_bf16 v[32:47], v[192:195], v[10:13], v[32:47]
	ds_read_b64_tr_b16 v[10:11], v0 offset:0x2600
	ds_read_b64_tr_b16 v[12:13], v0 offset:0x2e00
	s_waitcnt lgkmcnt(6)
	v_mfma_f32_32x32x16_bf16 v[32:47], v[196:199], v[80:83], v[32:47]
	ds_read_b64_tr_b16 v[80:81], v0 offset:0x3600
	ds_read_b64_tr_b16 v[82:83], v0 offset:0x3e00
	s_waitcnt lgkmcnt(6)
	v_mfma_f32_32x32x16_bf16 v[16:31], v[184:187], v[2:5], v[16:31]
	s_waitcnt lgkmcnt(4)
	v_mfma_f32_32x32x16_bf16 v[16:31], v[188:191], v[6:9], v[16:31]
	s_waitcnt lgkmcnt(2)
	v_mfma_f32_32x32x16_bf16 v[16:31], v[192:195], v[10:13], v[16:31]
	s_waitcnt lgkmcnt(0)
	v_mfma_f32_32x32x16_bf16 v[16:31], v[196:199], v[80:83], v[16:31]
	s_setprio 0
	s_add_i32 s2, s34, -2
	s_and_b32 s2, s2, 3
	s_lshl_b32 s3, s2, 14
	s_add_i32 s3, s3, 0
	s_waitcnt lgkmcnt(0)
	s_barrier
	v_add_u32_e32 v0, s3, v233
	s_add_i32 s35, s34, -1
	s_waitcnt vmcnt(2)
	ds_write_b128 v0, v[172:175]
	v_add_u32_e32 v0, s3, v234
	s_cmp_lt_u32 s35, s45
	s_waitcnt vmcnt(1)
	ds_write_b128 v0, v[176:179]
	v_lshl_add_u32 v0, s2, 13, v235
	s_cselect_b64 s[2:3], -1, 0
	s_cmp_ge_u32 s35, s45
	s_waitcnt vmcnt(0)
	ds_write_b128 v0, v[180:183]
	s_cbranch_scc1 .LBB0_624
	s_add_u32 s4, s36, 0xef40000
	s_addc_u32 s5, s37, 0
	v_lshl_add_u64 v[2:3], v[218:219], 0, s[4:5]
	s_add_u32 s4, s4, 0x8000
	s_addc_u32 s5, s5, 0
	v_lshl_add_u64 v[4:5], v[218:219], 0, s[4:5]
	global_load_dwordx4 v[160:163], v[2:3], off
	global_load_dwordx4 v[164:167], v[4:5], off
	s_add_u32 s4, s36, 0xcf40000
	s_addc_u32 s5, s37, 0
	v_lshl_add_u64 v[2:3], v[216:217], 0, s[4:5]
	global_load_dwordx4 v[168:171], v[2:3], off offset:128

; #define SLOAD(i, k0) do { sr_[i].vs0 = *(const bf16x8*)(&Vh[(size_t)((k0) + sr) * LDX + sc]); sr_[i].vs1 = *(const bf16x8*)(&Vh[(size_t)((k0) + 32 + sr) * LDX + sc]); \
;     sr_[i].ks0 = *(const bf16x8*)(&Kh[(size_t)((k0) + kr) * LDX + kc]); } while (0)
; __device__ __forceinline__ void attn_pass(const bf16_t* __restrict__ Qb, const bf16_t* __restrict__ Kh, const bf16_t* __restrict__ Vh, int seq, LAS char* lds, const int wid, f32x16 (&o)[4], float (&rli)[16]) {
;     ...
;         if (j + 4 < NT) SLOAD(1, (j + 4) * KVBLK);
.LBB0_631:
	s_cmp_ge_u32 s34, s45
	s_cbranch_scc1 .LBB0_633
	s_add_u32 s4, s36, 0xef50000
	s_addc_u32 s5, s37, 0
	v_lshl_add_u64 v[2:3], v[218:219], 0, s[4:5]
	s_add_u32 s4, s4, 0x8000
	s_addc_u32 s5, s5, 0
	v_lshl_add_u64 v[4:5], v[218:219], 0, s[4:5]
	global_load_dwordx4 v[172:175], v[2:3], off
	global_load_dwordx4 v[176:179], v[4:5], off
	s_add_u32 s4, s36, 0xcf50000
	s_addc_u32 s5, s37, 0
	v_lshl_add_u64 v[2:3], v[216:217], 0, s[4:5]
	global_load_dwordx4 v[180:183], v[2:3], off offset:128
